# tail transposes config B (10/10/9.6 items per wave, od_w_out converted in P0) + stagger
# baseline (speedup 1.0000x reference)
.LBB0_73:
	s_mov_b32 s99, 0xc800
	s_cmp_eq_u32 s87, 0x100
	s_cselect_b32 s99, 0x4800, s99
	s_add_i32 s98, s99, -1
	s_lshl_b32 s0, s96, 3
	s_add_i32 s20, s93, s0
	s_cmp_gt_i32 s20, s98
	s_waitcnt lgkmcnt(0)
	s_barrier
	s_cbranch_scc1 .LBB0_158
	s_cmpk_gt_i32 s20, 0x1fff
	s_cbranch_scc0 .LBB0_80
	s_cmpk_gt_u32 s20, 0x27ff
	s_cbranch_scc0 .LBB0_81
	s_cmpk_gt_u32 s20, 0x3fff
	s_cbranch_scc0 .LBB0_82
	s_cmpk_gt_u32 s20, 0x47ff
	s_cbranch_scc0 .LBB0_83
	s_cmpk_gt_u32 s20, 0x87ff
	s_cbranch_scc0 .LBB0_84
	v_readlane_b32 s36, v244, 19
	s_add_i32 s4, s20, 0xffff7800
	v_readlane_b32 s37, v244, 20
	s_lshr_b32 s0, s4, 13
	s_mov_b32 s1, 0
	v_readlane_b32 s38, v244, 21
	v_readlane_b32 s39, v244, 22
	v_readlane_b32 s40, v244, 23
	v_readlane_b32 s41, v244, 24
	v_readlane_b32 s42, v244, 25
	v_readlane_b32 s43, v244, 26
	s_mov_b64 s[12:13], s[36:37]
	s_lshl_b64 s[2:3], s[0:1], 26
	s_mov_b64 s[14:15], s[38:39]
	s_add_u32 s2, s14, s2
	s_addc_u32 s3, s15, s3
	s_lshl_b64 s[0:1], s[0:1], 25
	s_add_u32 s0, s76, s0
	s_addc_u32 s1, s77, s1
	s_add_u32 s0, s0, 0x8989000
	v_readlane_b32 s44, v244, 27
	v_readlane_b32 s45, v244, 28
	v_readlane_b32 s46, v244, 29
	v_readlane_b32 s47, v244, 30
	v_readlane_b32 s48, v244, 31
	v_readlane_b32 s49, v244, 32
	v_readlane_b32 s50, v244, 33
	v_readlane_b32 s51, v244, 34
	s_mov_b64 s[16:17], s[40:41]
	s_mov_b64 s[18:19], s[42:43]
	s_addc_u32 s1, s1, 0
	s_and_b32 s21, s4, 0x1fff
	s_mov_b64 s[4:5], 0
	s_branch .LBB0_85

.LBB0_363:
	s_waitcnt vmcnt(0)
	s_barrier
	s_cmp_lg_u32 s87, 0x100
	s_cbranch_scc1 .Ltt2_0_done
	s_cmp_lt_u32 s96, 128
	s_cbranch_scc1 .Ltt2_0_done
	s_cmp_ge_u32 s96, 256
	s_cbranch_scc1 .Ltt2_0_done
	s_sub_u32 s20, s96, 128
	s_lshl_b32 s20, s20, 3
	s_add_u32 s20, s20, s93
	s_movk_i32 s23, 1024
	v_mbcnt_hi_u32_b32 v0, -1, v212
	v_and_b32_e32 v0, 63, v0
	v_lshrrev_b32_e32 v1, 3, v0
	v_and_b32_e32 v2, 7, v0
	s_lshl_b32 s25, s93, 14
	v_mul_u32_u24_e32 v3, 0x84, v1
	v_mul_u32_u24_e32 v4, 0x420, v2
	v_lshlrev_b32_e32 v2, 4, v2
	v_add3_u32 v3, v3, v2, s25
	v_lshl_add_u32 v4, v1, 2, v4
	v_add_u32_e32 v4, s25, v4
	v_and_b32_e32 v7, 4, v1
	v_and_b32_e32 v5, 3, v1
	v_lshl_add_u32 v7, v7, 1, v5
	v_readlane_b32 s62, v245, 0
	v_readlane_b32 s63, v245, 1
	s_add_u32 s64, s76, 0x4989000
	s_addc_u32 s65, s77, 0
	v_readlane_b32 s66, v244, 21
	v_readlane_b32 s67, v244, 22
	s_add_u32 s68, s76, 0x8989000
	s_addc_u32 s69, s77, 0
	s_cmp_ge_u32 s20, 10240
	s_cbranch_scc1 .Ltt2_0_done
	s_cmp_lt_u32 s20, 8192
	s_cbranch_scc1 .Ltt2_0_r1_s0
	s_sub_u32 s25, s20, 8192
	s_lshr_b32 s27, s25, 6
	s_and_b32 s31, s25, 63
	s_mul_i32 s35, s27, 0x80000
	s_lshl_b32 s41, s31, 7
	s_add_u32 s35, s35, s41
	s_add_u32 s0, s66, s35
	s_addc_u32 s1, s67, 0
	s_mul_i32 s35, s31, 0x80000
	s_lshl_b32 s41, s27, 7
	s_add_u32 s35, s35, s41
	s_add_u32 s2, s68, s35
	s_addc_u32 s3, s69, 0
	s_mov_b32 s5, 0x2000
	s_mov_b32 s6, 0x10000
	s_mov_b32 s7, 0x4000
	s_branch .Ltt2_0_r1_e

.Ltt2_0_r1_e:
	v_mad_u32_u24 v5, v1, s5, v2
	global_load_dwordx4 v[8:11], v5, s[0:1] nt
	s_add_u32 s0, s0, s6
	s_addc_u32 s1, s1, 0
	global_load_dwordx4 v[12:15], v5, s[0:1] nt
	s_add_u32 s0, s0, s6
	s_addc_u32 s1, s1, 0
	global_load_dwordx4 v[16:19], v5, s[0:1] nt
	s_add_u32 s0, s0, s6
	s_addc_u32 s1, s1, 0
	global_load_dwordx4 v[20:23], v5, s[0:1] nt
	s_add_u32 s0, s0, s6
	s_addc_u32 s1, s1, 0
	global_load_dwordx4 v[24:27], v5, s[0:1] nt
	s_add_u32 s0, s0, s6
	s_addc_u32 s1, s1, 0
	global_load_dwordx4 v[28:31], v5, s[0:1] nt
	s_add_u32 s0, s0, s6
	s_addc_u32 s1, s1, 0
	global_load_dwordx4 v[32:35], v5, s[0:1] nt
	s_add_u32 s0, s0, s6
	s_addc_u32 s1, s1, 0
	global_load_dwordx4 v[36:39], v5, s[0:1] nt
	s_add_u32 s0, s0, s6
	s_addc_u32 s1, s1, 0
	s_add_u32 s20, s20, s23
	s_cmp_ge_u32 s20, 10240
	s_cbranch_scc1 .Ltt2_0_dr1
	s_cmp_lt_u32 s20, 8192
	s_cbranch_scc1 .Ltt2_0_r2_s0
	s_sub_u32 s25, s20, 8192
	s_lshr_b32 s27, s25, 6
	s_and_b32 s31, s25, 63
	s_mul_i32 s35, s27, 0x80000
	s_lshl_b32 s41, s31, 7
	s_add_u32 s35, s35, s41
	s_add_u32 s0, s66, s35
	s_addc_u32 s1, s67, 0
	s_mul_i32 s35, s31, 0x80000
	s_lshl_b32 s41, s27, 7
	s_add_u32 s35, s35, s41
	s_add_u32 s10, s68, s35
	s_addc_u32 s11, s69, 0
	s_mov_b32 s5, 0x2000
	s_mov_b32 s6, 0x10000
	s_mov_b32 s47, 0x4000
	s_branch .Ltt2_0_r2_e

.Ltt2_0_r2_e:
	v_mad_u32_u24 v5, v1, s5, v2
	global_load_dwordx4 v[40:43], v5, s[0:1] nt
	s_add_u32 s0, s0, s6
	s_addc_u32 s1, s1, 0
	global_load_dwordx4 v[44:47], v5, s[0:1] nt
	s_add_u32 s0, s0, s6
	s_addc_u32 s1, s1, 0
	global_load_dwordx4 v[48:51], v5, s[0:1] nt
	s_add_u32 s0, s0, s6
	s_addc_u32 s1, s1, 0
	global_load_dwordx4 v[52:55], v5, s[0:1] nt
	s_add_u32 s0, s0, s6
	s_addc_u32 s1, s1, 0
	global_load_dwordx4 v[56:59], v5, s[0:1] nt
	s_add_u32 s0, s0, s6
	s_addc_u32 s1, s1, 0
	global_load_dwordx4 v[60:63], v5, s[0:1] nt
	s_add_u32 s0, s0, s6
	s_addc_u32 s1, s1, 0
	global_load_dwordx4 v[64:67], v5, s[0:1] nt
	s_add_u32 s0, s0, s6
	s_addc_u32 s1, s1, 0
	global_load_dwordx4 v[68:71], v5, s[0:1] nt
	s_add_u32 s0, s0, s6
	s_addc_u32 s1, s1, 0
	s_add_u32 s20, s20, s23
	s_cmp_ge_u32 s20, 10240
	s_cbranch_scc1 .Ltt2_0_dr2
	s_cmp_lt_u32 s20, 8192
	s_cbranch_scc1 .Ltt2_0_r3_s0
	s_sub_u32 s25, s20, 8192
	s_lshr_b32 s27, s25, 6
	s_and_b32 s31, s25, 63
	s_mul_i32 s35, s27, 0x80000
	s_lshl_b32 s41, s31, 7
	s_add_u32 s35, s35, s41
	s_add_u32 s0, s66, s35
	s_addc_u32 s1, s67, 0
	s_mul_i32 s35, s31, 0x80000
	s_lshl_b32 s41, s27, 7
	s_add_u32 s35, s35, s41
	s_add_u32 s42, s68, s35
	s_addc_u32 s43, s69, 0
	s_mov_b32 s5, 0x2000
	s_mov_b32 s6, 0x10000
	s_mov_b32 s44, 0x4000
	s_branch .Ltt2_0_r3_e

.Ltt2_0_r3_e:
	v_mad_u32_u24 v5, v1, s5, v2
	global_load_dwordx4 v[72:75], v5, s[0:1] nt
	s_add_u32 s0, s0, s6
	s_addc_u32 s1, s1, 0
	global_load_dwordx4 v[76:79], v5, s[0:1] nt
	s_add_u32 s0, s0, s6
	s_addc_u32 s1, s1, 0
	global_load_dwordx4 v[80:83], v5, s[0:1] nt
	s_add_u32 s0, s0, s6
	s_addc_u32 s1, s1, 0
	global_load_dwordx4 v[84:87], v5, s[0:1] nt
	s_add_u32 s0, s0, s6
	s_addc_u32 s1, s1, 0
	global_load_dwordx4 v[88:91], v5, s[0:1] nt
	s_add_u32 s0, s0, s6
	s_addc_u32 s1, s1, 0
	global_load_dwordx4 v[92:95], v5, s[0:1] nt
	s_add_u32 s0, s0, s6
	s_addc_u32 s1, s1, 0
	global_load_dwordx4 v[96:99], v5, s[0:1] nt
	s_add_u32 s0, s0, s6
	s_addc_u32 s1, s1, 0
	global_load_dwordx4 v[100:103], v5, s[0:1] nt
	s_add_u32 s0, s0, s6
	s_addc_u32 s1, s1, 0
	s_add_u32 s20, s20, s23
	s_waitcnt vmcnt(16)
	ds_write_b32 v3, v8 offset:0
	ds_write_b32 v3, v9 offset:4
	ds_write_b32 v3, v10 offset:8
	ds_write_b32 v3, v11 offset:12
	ds_write_b32 v3, v12 offset:1056
	ds_write_b32 v3, v13 offset:1060
	ds_write_b32 v3, v14 offset:1064
	ds_write_b32 v3, v15 offset:1068
	ds_write_b32 v3, v16 offset:2112
	ds_write_b32 v3, v17 offset:2116
	ds_write_b32 v3, v18 offset:2120
	ds_write_b32 v3, v19 offset:2124
	ds_write_b32 v3, v20 offset:3168
	ds_write_b32 v3, v21 offset:3172
	ds_write_b32 v3, v22 offset:3176
	ds_write_b32 v3, v23 offset:3180
	ds_write_b32 v3, v24 offset:4224
	ds_write_b32 v3, v25 offset:4228
	ds_write_b32 v3, v26 offset:4232
	ds_write_b32 v3, v27 offset:4236
	ds_write_b32 v3, v28 offset:5280
	ds_write_b32 v3, v29 offset:5284
	ds_write_b32 v3, v30 offset:5288
	ds_write_b32 v3, v31 offset:5292
	ds_write_b32 v3, v32 offset:6336
	ds_write_b32 v3, v33 offset:6340
	ds_write_b32 v3, v34 offset:6344
	ds_write_b32 v3, v35 offset:6348
	ds_write_b32 v3, v36 offset:7392
	ds_write_b32 v3, v37 offset:7396
	ds_write_b32 v3, v38 offset:7400
	ds_write_b32 v3, v39 offset:7404
	s_mov_b32 s32, s2
	s_mov_b32 s33, s3
	s_lshl_b32 s49, s7, 3
	v_mad_u32_u24 v6, v1, s7, v2
	s_waitcnt lgkmcnt(0)
	ds_read_b32 v104, v4 offset:0
	ds_read_b32 v105, v4 offset:132
	ds_read_b32 v106, v4 offset:264
	ds_read_b32 v107, v4 offset:396
	ds_read_b32 v108, v4 offset:528
	ds_read_b32 v109, v4 offset:660
	ds_read_b32 v110, v4 offset:792
	ds_read_b32 v111, v4 offset:924
	ds_read_b32 v112, v4 offset:32
	ds_read_b32 v113, v4 offset:164
	ds_read_b32 v114, v4 offset:296
	ds_read_b32 v115, v4 offset:428
	ds_read_b32 v116, v4 offset:560
	ds_read_b32 v117, v4 offset:692
	ds_read_b32 v118, v4 offset:824
	ds_read_b32 v119, v4 offset:956
	s_waitcnt lgkmcnt(8)
	v_cvt_pk_bf16_f32 v136, v104, v105
	v_cvt_pk_bf16_f32 v137, v106, v107
	v_cvt_pk_bf16_f32 v138, v108, v109
	v_cvt_pk_bf16_f32 v139, v110, v111
	global_store_dwordx4 v6, v[136:139], s[32:33] nt
	s_add_u32 s32, s32, s49
	s_addc_u32 s33, s33, 0
	ds_read_b32 v120, v4 offset:64
	ds_read_b32 v121, v4 offset:196
	ds_read_b32 v122, v4 offset:328
	ds_read_b32 v123, v4 offset:460
	ds_read_b32 v124, v4 offset:592
	ds_read_b32 v125, v4 offset:724
	ds_read_b32 v126, v4 offset:856
	ds_read_b32 v127, v4 offset:988
	s_waitcnt lgkmcnt(8)
	v_cvt_pk_bf16_f32 v140, v112, v113
	v_cvt_pk_bf16_f32 v141, v114, v115
	v_cvt_pk_bf16_f32 v142, v116, v117
	v_cvt_pk_bf16_f32 v143, v118, v119
	global_store_dwordx4 v6, v[140:143], s[32:33] nt
	s_add_u32 s32, s32, s49
	s_addc_u32 s33, s33, 0
	ds_read_b32 v128, v4 offset:96
	ds_read_b32 v129, v4 offset:228
	ds_read_b32 v130, v4 offset:360
	ds_read_b32 v131, v4 offset:492
	ds_read_b32 v132, v4 offset:624
	ds_read_b32 v133, v4 offset:756
	ds_read_b32 v134, v4 offset:888
	ds_read_b32 v135, v4 offset:1020
	s_waitcnt lgkmcnt(8)
	v_cvt_pk_bf16_f32 v136, v120, v121
	v_cvt_pk_bf16_f32 v137, v122, v123
	v_cvt_pk_bf16_f32 v138, v124, v125
	v_cvt_pk_bf16_f32 v139, v126, v127
	global_store_dwordx4 v6, v[136:139], s[32:33] nt
	s_add_u32 s32, s32, s49
	s_addc_u32 s33, s33, 0
	s_waitcnt lgkmcnt(0)
	v_cvt_pk_bf16_f32 v140, v128, v129
	v_cvt_pk_bf16_f32 v141, v130, v131
	v_cvt_pk_bf16_f32 v142, v132, v133
	v_cvt_pk_bf16_f32 v143, v134, v135
	global_store_dwordx4 v6, v[140:143], s[32:33] nt
	s_add_u32 s32, s32, s49
	s_addc_u32 s33, s33, 0
	s_cmp_ge_u32 s20, 10240
	s_cbranch_scc1 .Ltt2_0_dr3
	s_cmp_lt_u32 s20, 8192
	s_cbranch_scc1 .Ltt2_0_r4_s0
	s_sub_u32 s25, s20, 8192
	s_lshr_b32 s27, s25, 6
	s_and_b32 s31, s25, 63
	s_mul_i32 s35, s27, 0x80000
	s_lshl_b32 s41, s31, 7
	s_add_u32 s35, s35, s41
	s_add_u32 s0, s66, s35
	s_addc_u32 s1, s67, 0
	s_mul_i32 s35, s31, 0x80000
	s_lshl_b32 s41, s27, 7
	s_add_u32 s35, s35, s41
	s_add_u32 s2, s68, s35
	s_addc_u32 s3, s69, 0
	s_mov_b32 s5, 0x2000
	s_mov_b32 s6, 0x10000
	s_mov_b32 s7, 0x4000
	s_branch .Ltt2_0_r4_e

.Ltt2_0_loop:
	s_cmp_ge_u32 s20, 10240
	s_cbranch_scc1 .Ltt2_0_dr4
	s_cmp_lt_u32 s20, 8192
	s_cbranch_scc1 .Ltt2_0_r5_s0
	s_sub_u32 s25, s20, 8192
	s_lshr_b32 s27, s25, 6
	s_and_b32 s31, s25, 63
	s_mul_i32 s35, s27, 0x80000
	s_lshl_b32 s41, s31, 7
	s_add_u32 s35, s35, s41
	s_add_u32 s0, s66, s35
	s_addc_u32 s1, s67, 0
	s_mul_i32 s35, s31, 0x80000
	s_lshl_b32 s41, s27, 7
	s_add_u32 s35, s35, s41
	s_add_u32 s10, s68, s35
	s_addc_u32 s11, s69, 0
	s_mov_b32 s5, 0x2000
	s_mov_b32 s6, 0x10000
	s_mov_b32 s47, 0x4000
	s_branch .Ltt2_0_r5_e

.Ltt2_0_r5_e:
	v_mad_u32_u24 v5, v1, s5, v2
	global_load_dwordx4 v[40:43], v5, s[0:1] nt
	s_add_u32 s0, s0, s6
	s_addc_u32 s1, s1, 0
	global_load_dwordx4 v[44:47], v5, s[0:1] nt
	s_add_u32 s0, s0, s6
	s_addc_u32 s1, s1, 0
	global_load_dwordx4 v[48:51], v5, s[0:1] nt
	s_add_u32 s0, s0, s6
	s_addc_u32 s1, s1, 0
	global_load_dwordx4 v[52:55], v5, s[0:1] nt
	s_add_u32 s0, s0, s6
	s_addc_u32 s1, s1, 0
	global_load_dwordx4 v[56:59], v5, s[0:1] nt
	s_add_u32 s0, s0, s6
	s_addc_u32 s1, s1, 0
	global_load_dwordx4 v[60:63], v5, s[0:1] nt
	s_add_u32 s0, s0, s6
	s_addc_u32 s1, s1, 0
	global_load_dwordx4 v[64:67], v5, s[0:1] nt
	s_add_u32 s0, s0, s6
	s_addc_u32 s1, s1, 0
	global_load_dwordx4 v[68:71], v5, s[0:1] nt
	s_add_u32 s0, s0, s6
	s_addc_u32 s1, s1, 0
	s_add_u32 s20, s20, s23
	s_waitcnt vmcnt(24)
	ds_write_b32 v3, v72 offset:0
	ds_write_b32 v3, v73 offset:4
	ds_write_b32 v3, v74 offset:8
	ds_write_b32 v3, v75 offset:12
	ds_write_b32 v3, v76 offset:1056
	ds_write_b32 v3, v77 offset:1060
	ds_write_b32 v3, v78 offset:1064
	ds_write_b32 v3, v79 offset:1068
	ds_write_b32 v3, v80 offset:2112
	ds_write_b32 v3, v81 offset:2116
	ds_write_b32 v3, v82 offset:2120
	ds_write_b32 v3, v83 offset:2124
	ds_write_b32 v3, v84 offset:3168
	ds_write_b32 v3, v85 offset:3172
	ds_write_b32 v3, v86 offset:3176
	ds_write_b32 v3, v87 offset:3180
	ds_write_b32 v3, v88 offset:4224
	ds_write_b32 v3, v89 offset:4228
	ds_write_b32 v3, v90 offset:4232
	ds_write_b32 v3, v91 offset:4236
	ds_write_b32 v3, v92 offset:5280
	ds_write_b32 v3, v93 offset:5284
	ds_write_b32 v3, v94 offset:5288
	ds_write_b32 v3, v95 offset:5292
	ds_write_b32 v3, v96 offset:6336
	ds_write_b32 v3, v97 offset:6340
	ds_write_b32 v3, v98 offset:6344
	ds_write_b32 v3, v99 offset:6348
	ds_write_b32 v3, v100 offset:7392
	ds_write_b32 v3, v101 offset:7396
	ds_write_b32 v3, v102 offset:7400
	ds_write_b32 v3, v103 offset:7404
	s_mov_b32 s32, s42
	s_mov_b32 s33, s43
	s_lshl_b32 s49, s44, 3
	v_mad_u32_u24 v6, v1, s44, v2
	s_waitcnt lgkmcnt(0)
	ds_read_b32 v104, v4 offset:0
	ds_read_b32 v105, v4 offset:132
	ds_read_b32 v106, v4 offset:264
	ds_read_b32 v107, v4 offset:396
	ds_read_b32 v108, v4 offset:528
	ds_read_b32 v109, v4 offset:660
	ds_read_b32 v110, v4 offset:792
	ds_read_b32 v111, v4 offset:924
	ds_read_b32 v112, v4 offset:32
	ds_read_b32 v113, v4 offset:164
	ds_read_b32 v114, v4 offset:296
	ds_read_b32 v115, v4 offset:428
	ds_read_b32 v116, v4 offset:560
	ds_read_b32 v117, v4 offset:692
	ds_read_b32 v118, v4 offset:824
	ds_read_b32 v119, v4 offset:956
	s_waitcnt lgkmcnt(8)
	v_cvt_pk_bf16_f32 v136, v104, v105
	v_cvt_pk_bf16_f32 v137, v106, v107
	v_cvt_pk_bf16_f32 v138, v108, v109
	v_cvt_pk_bf16_f32 v139, v110, v111
	global_store_dwordx4 v6, v[136:139], s[32:33] nt
	s_add_u32 s32, s32, s49
	s_addc_u32 s33, s33, 0
	ds_read_b32 v120, v4 offset:64
	ds_read_b32 v121, v4 offset:196
	ds_read_b32 v122, v4 offset:328
	ds_read_b32 v123, v4 offset:460
	ds_read_b32 v124, v4 offset:592
	ds_read_b32 v125, v4 offset:724
	ds_read_b32 v126, v4 offset:856
	ds_read_b32 v127, v4 offset:988
	s_waitcnt lgkmcnt(8)
	v_cvt_pk_bf16_f32 v140, v112, v113
	v_cvt_pk_bf16_f32 v141, v114, v115
	v_cvt_pk_bf16_f32 v142, v116, v117
	v_cvt_pk_bf16_f32 v143, v118, v119
	global_store_dwordx4 v6, v[140:143], s[32:33] nt
	s_add_u32 s32, s32, s49
	s_addc_u32 s33, s33, 0
	ds_read_b32 v128, v4 offset:96
	ds_read_b32 v129, v4 offset:228
	ds_read_b32 v130, v4 offset:360
	ds_read_b32 v131, v4 offset:492
	ds_read_b32 v132, v4 offset:624
	ds_read_b32 v133, v4 offset:756
	ds_read_b32 v134, v4 offset:888
	ds_read_b32 v135, v4 offset:1020
	s_waitcnt lgkmcnt(8)
	v_cvt_pk_bf16_f32 v136, v120, v121
	v_cvt_pk_bf16_f32 v137, v122, v123
	v_cvt_pk_bf16_f32 v138, v124, v125
	v_cvt_pk_bf16_f32 v139, v126, v127
	global_store_dwordx4 v6, v[136:139], s[32:33] nt
	s_add_u32 s32, s32, s49
	s_addc_u32 s33, s33, 0
	s_waitcnt lgkmcnt(0)
	v_cvt_pk_bf16_f32 v140, v128, v129
	v_cvt_pk_bf16_f32 v141, v130, v131
	v_cvt_pk_bf16_f32 v142, v132, v133
	v_cvt_pk_bf16_f32 v143, v134, v135
	global_store_dwordx4 v6, v[140:143], s[32:33] nt
	s_add_u32 s32, s32, s49
	s_addc_u32 s33, s33, 0
	s_cmp_ge_u32 s20, 10240
	s_cbranch_scc1 .Ltt2_0_dr5
	s_cmp_lt_u32 s20, 8192
	s_cbranch_scc1 .Ltt2_0_r6_s0
	s_sub_u32 s25, s20, 8192
	s_lshr_b32 s27, s25, 6
	s_and_b32 s31, s25, 63
	s_mul_i32 s35, s27, 0x80000
	s_lshl_b32 s41, s31, 7
	s_add_u32 s35, s35, s41
	s_add_u32 s0, s66, s35
	s_addc_u32 s1, s67, 0
	s_mul_i32 s35, s31, 0x80000
	s_lshl_b32 s41, s27, 7
	s_add_u32 s35, s35, s41
	s_add_u32 s42, s68, s35
	s_addc_u32 s43, s69, 0
	s_mov_b32 s5, 0x2000
	s_mov_b32 s6, 0x10000
	s_mov_b32 s44, 0x4000
	s_branch .Ltt2_0_r6_e

.Ltt2_0_r6_e:
	v_mad_u32_u24 v5, v1, s5, v2
	global_load_dwordx4 v[72:75], v5, s[0:1] nt
	s_add_u32 s0, s0, s6
	s_addc_u32 s1, s1, 0
	global_load_dwordx4 v[76:79], v5, s[0:1] nt
	s_add_u32 s0, s0, s6
	s_addc_u32 s1, s1, 0
	global_load_dwordx4 v[80:83], v5, s[0:1] nt
	s_add_u32 s0, s0, s6
	s_addc_u32 s1, s1, 0
	global_load_dwordx4 v[84:87], v5, s[0:1] nt
	s_add_u32 s0, s0, s6
	s_addc_u32 s1, s1, 0
	global_load_dwordx4 v[88:91], v5, s[0:1] nt
	s_add_u32 s0, s0, s6
	s_addc_u32 s1, s1, 0
	global_load_dwordx4 v[92:95], v5, s[0:1] nt
	s_add_u32 s0, s0, s6
	s_addc_u32 s1, s1, 0
	global_load_dwordx4 v[96:99], v5, s[0:1] nt
	s_add_u32 s0, s0, s6
	s_addc_u32 s1, s1, 0
	global_load_dwordx4 v[100:103], v5, s[0:1] nt
	s_add_u32 s0, s0, s6
	s_addc_u32 s1, s1, 0
	s_add_u32 s20, s20, s23
	s_waitcnt vmcnt(24)
	ds_write_b32 v3, v8 offset:0
	ds_write_b32 v3, v9 offset:4
	ds_write_b32 v3, v10 offset:8
	ds_write_b32 v3, v11 offset:12
	ds_write_b32 v3, v12 offset:1056
	ds_write_b32 v3, v13 offset:1060
	ds_write_b32 v3, v14 offset:1064
	ds_write_b32 v3, v15 offset:1068
	ds_write_b32 v3, v16 offset:2112
	ds_write_b32 v3, v17 offset:2116
	ds_write_b32 v3, v18 offset:2120
	ds_write_b32 v3, v19 offset:2124
	ds_write_b32 v3, v20 offset:3168
	ds_write_b32 v3, v21 offset:3172
	ds_write_b32 v3, v22 offset:3176
	ds_write_b32 v3, v23 offset:3180
	ds_write_b32 v3, v24 offset:4224
	ds_write_b32 v3, v25 offset:4228
	ds_write_b32 v3, v26 offset:4232
	ds_write_b32 v3, v27 offset:4236
	ds_write_b32 v3, v28 offset:5280
	ds_write_b32 v3, v29 offset:5284
	ds_write_b32 v3, v30 offset:5288
	ds_write_b32 v3, v31 offset:5292
	ds_write_b32 v3, v32 offset:6336
	ds_write_b32 v3, v33 offset:6340
	ds_write_b32 v3, v34 offset:6344
	ds_write_b32 v3, v35 offset:6348
	ds_write_b32 v3, v36 offset:7392
	ds_write_b32 v3, v37 offset:7396
	ds_write_b32 v3, v38 offset:7400
	ds_write_b32 v3, v39 offset:7404
	s_mov_b32 s32, s2
	s_mov_b32 s33, s3
	s_lshl_b32 s49, s7, 3
	v_mad_u32_u24 v6, v1, s7, v2
	s_waitcnt lgkmcnt(0)
	ds_read_b32 v104, v4 offset:0
	ds_read_b32 v105, v4 offset:132
	ds_read_b32 v106, v4 offset:264
	ds_read_b32 v107, v4 offset:396
	ds_read_b32 v108, v4 offset:528
	ds_read_b32 v109, v4 offset:660
	ds_read_b32 v110, v4 offset:792
	ds_read_b32 v111, v4 offset:924
	ds_read_b32 v112, v4 offset:32
	ds_read_b32 v113, v4 offset:164
	ds_read_b32 v114, v4 offset:296
	ds_read_b32 v115, v4 offset:428
	ds_read_b32 v116, v4 offset:560
	ds_read_b32 v117, v4 offset:692
	ds_read_b32 v118, v4 offset:824
	ds_read_b32 v119, v4 offset:956
	s_waitcnt lgkmcnt(8)
	v_cvt_pk_bf16_f32 v136, v104, v105
	v_cvt_pk_bf16_f32 v137, v106, v107
	v_cvt_pk_bf16_f32 v138, v108, v109
	v_cvt_pk_bf16_f32 v139, v110, v111
	global_store_dwordx4 v6, v[136:139], s[32:33] nt
	s_add_u32 s32, s32, s49
	s_addc_u32 s33, s33, 0
	ds_read_b32 v120, v4 offset:64
	ds_read_b32 v121, v4 offset:196
	ds_read_b32 v122, v4 offset:328
	ds_read_b32 v123, v4 offset:460
	ds_read_b32 v124, v4 offset:592
	ds_read_b32 v125, v4 offset:724
	ds_read_b32 v126, v4 offset:856
	ds_read_b32 v127, v4 offset:988
	s_waitcnt lgkmcnt(8)
	v_cvt_pk_bf16_f32 v140, v112, v113
	v_cvt_pk_bf16_f32 v141, v114, v115
	v_cvt_pk_bf16_f32 v142, v116, v117
	v_cvt_pk_bf16_f32 v143, v118, v119
	global_store_dwordx4 v6, v[140:143], s[32:33] nt
	s_add_u32 s32, s32, s49
	s_addc_u32 s33, s33, 0
	ds_read_b32 v128, v4 offset:96
	ds_read_b32 v129, v4 offset:228
	ds_read_b32 v130, v4 offset:360
	ds_read_b32 v131, v4 offset:492
	ds_read_b32 v132, v4 offset:624
	ds_read_b32 v133, v4 offset:756
	ds_read_b32 v134, v4 offset:888
	ds_read_b32 v135, v4 offset:1020
	s_waitcnt lgkmcnt(8)
	v_cvt_pk_bf16_f32 v136, v120, v121
	v_cvt_pk_bf16_f32 v137, v122, v123
	v_cvt_pk_bf16_f32 v138, v124, v125
	v_cvt_pk_bf16_f32 v139, v126, v127
	global_store_dwordx4 v6, v[136:139], s[32:33] nt
	s_add_u32 s32, s32, s49
	s_addc_u32 s33, s33, 0
	s_waitcnt lgkmcnt(0)
	v_cvt_pk_bf16_f32 v140, v128, v129
	v_cvt_pk_bf16_f32 v141, v130, v131
	v_cvt_pk_bf16_f32 v142, v132, v133
	v_cvt_pk_bf16_f32 v143, v134, v135
	global_store_dwordx4 v6, v[140:143], s[32:33] nt
	s_add_u32 s32, s32, s49
	s_addc_u32 s33, s33, 0
	s_cmp_ge_u32 s20, 10240
	s_cbranch_scc1 .Ltt2_0_dr6
	s_cmp_lt_u32 s20, 8192
	s_cbranch_scc1 .Ltt2_0_r7_s0
	s_sub_u32 s25, s20, 8192
	s_lshr_b32 s27, s25, 6
	s_and_b32 s31, s25, 63
	s_mul_i32 s35, s27, 0x80000
	s_lshl_b32 s41, s31, 7
	s_add_u32 s35, s35, s41
	s_add_u32 s0, s66, s35
	s_addc_u32 s1, s67, 0
	s_mul_i32 s35, s31, 0x80000
	s_lshl_b32 s41, s27, 7
	s_add_u32 s35, s35, s41
	s_add_u32 s2, s68, s35
	s_addc_u32 s3, s69, 0
	s_mov_b32 s5, 0x2000
	s_mov_b32 s6, 0x10000
	s_mov_b32 s7, 0x4000
	s_branch .Ltt2_0_r7_e

.LBB0_832:
	s_waitcnt vmcnt(0)
	s_barrier
	s_cmp_lg_u32 s87, 0x100
	s_cbranch_scc1 .Ltt7_0_done
	s_cmp_lt_u32 s96, 128
	s_cbranch_scc1 .Ltt7_0_done
	s_cmp_ge_u32 s96, 256
	s_cbranch_scc1 .Ltt7_0_done
	s_sub_u32 s20, s96, 128
	s_lshl_b32 s20, s20, 3
	s_add_u32 s20, s20, s93
	s_movk_i32 s23, 1024
	v_mbcnt_hi_u32_b32 v0, -1, v212
	v_and_b32_e32 v0, 63, v0
	v_lshrrev_b32_e32 v1, 3, v0
	v_and_b32_e32 v2, 7, v0
	s_lshl_b32 s25, s93, 14
	v_mul_u32_u24_e32 v3, 0x84, v1
	v_mul_u32_u24_e32 v4, 0x420, v2
	v_lshlrev_b32_e32 v2, 4, v2
	v_add3_u32 v3, v3, v2, s25
	v_lshl_add_u32 v4, v1, 2, v4
	v_add_u32_e32 v4, s25, v4
	v_and_b32_e32 v7, 4, v1
	v_and_b32_e32 v5, 3, v1
	v_lshl_add_u32 v7, v7, 1, v5
	v_readlane_b32 s62, v244, 21
	v_readlane_b32 s63, v244, 22
	s_add_u32 s64, s76, 0x8989000
	s_addc_u32 s65, s77, 0
	v_readlane_b32 s66, v245, 0
	v_readlane_b32 s67, v245, 1
	s_add_u32 s68, s76, 0x6989000
	s_addc_u32 s69, s77, 0
	s_nop 0
	s_add_u32 s66, s66, 0x4000000
	s_addc_u32 s67, s67, 0
	s_cmp_ge_u32 s20, 10240
	s_cbranch_scc1 .Ltt7_0_done
	s_cmp_lt_u32 s20, 6144
	s_cbranch_scc1 .Ltt7_0_r1_s0
	s_sub_u32 s25, s20, 6144
	s_lshr_b32 s27, s25, 8
	s_and_b32 s31, s25, 255
	s_mul_i32 s35, s27, 0x200000
	s_lshl_b32 s41, s31, 7
	s_add_u32 s35, s35, s41
	s_add_u32 s0, s66, s35
	s_addc_u32 s1, s67, 0
	s_mul_i32 s35, s31, 0x20000
	s_lshl_b32 s41, s27, 7
	s_add_u32 s35, s35, s41
	s_add_u32 s2, s68, s35
	s_addc_u32 s3, s69, 0
	s_mov_b32 s5, 0x8000
	s_mov_b32 s6, 0x40000
	s_mov_b32 s7, 0x1000
	s_branch .Ltt7_0_r1_e
.Ltt7_0_r1_s0:
	s_sub_u32 s25, s20, -2048
	s_lshr_b32 s27, s25, 6
	s_and_b32 s31, s25, 63
	s_mul_i32 s35, s27, 0x80000
	s_lshl_b32 s41, s31, 7
	s_add_u32 s35, s35, s41
	s_add_u32 s0, s62, s35
	s_addc_u32 s1, s63, 0
	s_mul_i32 s35, s31, 0x80000
	s_lshl_b32 s41, s27, 7
	s_add_u32 s35, s35, s41
	s_add_u32 s2, s64, s35
	s_addc_u32 s3, s65, 0
	s_mov_b32 s5, 0x2000
	s_mov_b32 s6, 0x10000
	s_mov_b32 s7, 0x4000
.Ltt7_0_r1_e:
	v_mad_u32_u24 v5, v1, s5, v2
	global_load_dwordx4 v[8:11], v5, s[0:1] nt
	s_add_u32 s0, s0, s6
	s_addc_u32 s1, s1, 0
	global_load_dwordx4 v[12:15], v5, s[0:1] nt
	s_add_u32 s0, s0, s6
	s_addc_u32 s1, s1, 0
	global_load_dwordx4 v[16:19], v5, s[0:1] nt
	s_add_u32 s0, s0, s6
	s_addc_u32 s1, s1, 0
	global_load_dwordx4 v[20:23], v5, s[0:1] nt
	s_add_u32 s0, s0, s6
	s_addc_u32 s1, s1, 0
	global_load_dwordx4 v[24:27], v5, s[0:1] nt
	s_add_u32 s0, s0, s6
	s_addc_u32 s1, s1, 0
	global_load_dwordx4 v[28:31], v5, s[0:1] nt
	s_add_u32 s0, s0, s6
	s_addc_u32 s1, s1, 0
	global_load_dwordx4 v[32:35], v5, s[0:1] nt
	s_add_u32 s0, s0, s6
	s_addc_u32 s1, s1, 0
	global_load_dwordx4 v[36:39], v5, s[0:1] nt
	s_add_u32 s0, s0, s6
	s_addc_u32 s1, s1, 0
	s_add_u32 s20, s20, s23
	s_cmp_ge_u32 s20, 10240
	s_cbranch_scc1 .Ltt7_0_dr1
	s_cmp_lt_u32 s20, 6144
	s_cbranch_scc1 .Ltt7_0_r2_s0
	s_sub_u32 s25, s20, 6144
	s_lshr_b32 s27, s25, 8
	s_and_b32 s31, s25, 255
	s_mul_i32 s35, s27, 0x200000
	s_lshl_b32 s41, s31, 7
	s_add_u32 s35, s35, s41
	s_add_u32 s0, s66, s35
	s_addc_u32 s1, s67, 0
	s_mul_i32 s35, s31, 0x20000
	s_lshl_b32 s41, s27, 7
	s_add_u32 s35, s35, s41
	s_add_u32 s10, s68, s35
	s_addc_u32 s11, s69, 0
	s_mov_b32 s5, 0x8000
	s_mov_b32 s6, 0x40000
	s_mov_b32 s47, 0x1000
	s_branch .Ltt7_0_r2_e
.Ltt7_0_r2_s0:
	s_sub_u32 s25, s20, -2048
	s_lshr_b32 s27, s25, 6
	s_and_b32 s31, s25, 63
	s_mul_i32 s35, s27, 0x80000
	s_lshl_b32 s41, s31, 7
	s_add_u32 s35, s35, s41
	s_add_u32 s0, s62, s35
	s_addc_u32 s1, s63, 0
	s_mul_i32 s35, s31, 0x80000
	s_lshl_b32 s41, s27, 7
	s_add_u32 s35, s35, s41
	s_add_u32 s10, s64, s35
	s_addc_u32 s11, s65, 0
	s_mov_b32 s5, 0x2000
	s_mov_b32 s6, 0x10000
	s_mov_b32 s47, 0x4000
.Ltt7_0_r2_e:
	v_mad_u32_u24 v5, v1, s5, v2
	global_load_dwordx4 v[40:43], v5, s[0:1] nt
	s_add_u32 s0, s0, s6
	s_addc_u32 s1, s1, 0
	global_load_dwordx4 v[44:47], v5, s[0:1] nt
	s_add_u32 s0, s0, s6
	s_addc_u32 s1, s1, 0
	global_load_dwordx4 v[48:51], v5, s[0:1] nt
	s_add_u32 s0, s0, s6
	s_addc_u32 s1, s1, 0
	global_load_dwordx4 v[52:55], v5, s[0:1] nt
	s_add_u32 s0, s0, s6
	s_addc_u32 s1, s1, 0
	global_load_dwordx4 v[56:59], v5, s[0:1] nt
	s_add_u32 s0, s0, s6
	s_addc_u32 s1, s1, 0
	global_load_dwordx4 v[60:63], v5, s[0:1] nt
	s_add_u32 s0, s0, s6
	s_addc_u32 s1, s1, 0
	global_load_dwordx4 v[64:67], v5, s[0:1] nt
	s_add_u32 s0, s0, s6
	s_addc_u32 s1, s1, 0
	global_load_dwordx4 v[68:71], v5, s[0:1] nt
	s_add_u32 s0, s0, s6
	s_addc_u32 s1, s1, 0
	s_add_u32 s20, s20, s23
	s_cmp_ge_u32 s20, 10240
	s_cbranch_scc1 .Ltt7_0_dr2
	s_cmp_lt_u32 s20, 6144
	s_cbranch_scc1 .Ltt7_0_r3_s0
	s_sub_u32 s25, s20, 6144
	s_lshr_b32 s27, s25, 8
	s_and_b32 s31, s25, 255
	s_mul_i32 s35, s27, 0x200000
	s_lshl_b32 s41, s31, 7
	s_add_u32 s35, s35, s41
	s_add_u32 s0, s66, s35
	s_addc_u32 s1, s67, 0
	s_mul_i32 s35, s31, 0x20000
	s_lshl_b32 s41, s27, 7
	s_add_u32 s35, s35, s41
	s_add_u32 s42, s68, s35
	s_addc_u32 s43, s69, 0
	s_mov_b32 s5, 0x8000
	s_mov_b32 s6, 0x40000
	s_mov_b32 s44, 0x1000
	s_branch .Ltt7_0_r3_e
.Ltt7_0_r3_s0:
	s_sub_u32 s25, s20, -2048
	s_lshr_b32 s27, s25, 6
	s_and_b32 s31, s25, 63
	s_mul_i32 s35, s27, 0x80000
	s_lshl_b32 s41, s31, 7
	s_add_u32 s35, s35, s41
	s_add_u32 s0, s62, s35
	s_addc_u32 s1, s63, 0
	s_mul_i32 s35, s31, 0x80000
	s_lshl_b32 s41, s27, 7
	s_add_u32 s35, s35, s41
	s_add_u32 s42, s64, s35
	s_addc_u32 s43, s65, 0
	s_mov_b32 s5, 0x2000
	s_mov_b32 s6, 0x10000
	s_mov_b32 s44, 0x4000
.Ltt7_0_r3_e:
	v_mad_u32_u24 v5, v1, s5, v2
	global_load_dwordx4 v[72:75], v5, s[0:1] nt
	s_add_u32 s0, s0, s6
	s_addc_u32 s1, s1, 0
	global_load_dwordx4 v[76:79], v5, s[0:1] nt
	s_add_u32 s0, s0, s6
	s_addc_u32 s1, s1, 0
	global_load_dwordx4 v[80:83], v5, s[0:1] nt
	s_add_u32 s0, s0, s6
	s_addc_u32 s1, s1, 0
	global_load_dwordx4 v[84:87], v5, s[0:1] nt
	s_add_u32 s0, s0, s6
	s_addc_u32 s1, s1, 0
	global_load_dwordx4 v[88:91], v5, s[0:1] nt
	s_add_u32 s0, s0, s6
	s_addc_u32 s1, s1, 0
	global_load_dwordx4 v[92:95], v5, s[0:1] nt
	s_add_u32 s0, s0, s6
	s_addc_u32 s1, s1, 0
	global_load_dwordx4 v[96:99], v5, s[0:1] nt
	s_add_u32 s0, s0, s6
	s_addc_u32 s1, s1, 0
	global_load_dwordx4 v[100:103], v5, s[0:1] nt
	s_add_u32 s0, s0, s6
	s_addc_u32 s1, s1, 0
	s_add_u32 s20, s20, s23
	s_waitcnt vmcnt(16)
	ds_write_b32 v3, v8 offset:0
	ds_write_b32 v3, v9 offset:4
	ds_write_b32 v3, v10 offset:8
	ds_write_b32 v3, v11 offset:12
	ds_write_b32 v3, v12 offset:1056
	ds_write_b32 v3, v13 offset:1060
	ds_write_b32 v3, v14 offset:1064
	ds_write_b32 v3, v15 offset:1068
	ds_write_b32 v3, v16 offset:2112
	ds_write_b32 v3, v17 offset:2116
	ds_write_b32 v3, v18 offset:2120
	ds_write_b32 v3, v19 offset:2124
	ds_write_b32 v3, v20 offset:3168
	ds_write_b32 v3, v21 offset:3172
	ds_write_b32 v3, v22 offset:3176
	ds_write_b32 v3, v23 offset:3180
	ds_write_b32 v3, v24 offset:4224
	ds_write_b32 v3, v25 offset:4228
	ds_write_b32 v3, v26 offset:4232
	ds_write_b32 v3, v27 offset:4236
	ds_write_b32 v3, v28 offset:5280
	ds_write_b32 v3, v29 offset:5284
	ds_write_b32 v3, v30 offset:5288
	ds_write_b32 v3, v31 offset:5292
	ds_write_b32 v3, v32 offset:6336
	ds_write_b32 v3, v33 offset:6340
	ds_write_b32 v3, v34 offset:6344
	ds_write_b32 v3, v35 offset:6348
	ds_write_b32 v3, v36 offset:7392
	ds_write_b32 v3, v37 offset:7396
	ds_write_b32 v3, v38 offset:7400
	ds_write_b32 v3, v39 offset:7404
	s_mov_b32 s32, s2
	s_mov_b32 s33, s3
	s_lshl_b32 s49, s7, 3
	v_mad_u32_u24 v6, v1, s7, v2
	s_waitcnt lgkmcnt(0)
	ds_read_b32 v104, v4 offset:0
	ds_read_b32 v105, v4 offset:132
	ds_read_b32 v106, v4 offset:264
	ds_read_b32 v107, v4 offset:396
	ds_read_b32 v108, v4 offset:528
	ds_read_b32 v109, v4 offset:660
	ds_read_b32 v110, v4 offset:792
	ds_read_b32 v111, v4 offset:924
	ds_read_b32 v112, v4 offset:32
	ds_read_b32 v113, v4 offset:164
	ds_read_b32 v114, v4 offset:296
	ds_read_b32 v115, v4 offset:428
	ds_read_b32 v116, v4 offset:560
	ds_read_b32 v117, v4 offset:692
	ds_read_b32 v118, v4 offset:824
	ds_read_b32 v119, v4 offset:956
	s_waitcnt lgkmcnt(8)
	v_cvt_pk_bf16_f32 v136, v104, v105
	v_cvt_pk_bf16_f32 v137, v106, v107
	v_cvt_pk_bf16_f32 v138, v108, v109
	v_cvt_pk_bf16_f32 v139, v110, v111
	global_store_dwordx4 v6, v[136:139], s[32:33] nt
	s_add_u32 s32, s32, s49
	s_addc_u32 s33, s33, 0
	ds_read_b32 v120, v4 offset:64
	ds_read_b32 v121, v4 offset:196
	ds_read_b32 v122, v4 offset:328
	ds_read_b32 v123, v4 offset:460
	ds_read_b32 v124, v4 offset:592
	ds_read_b32 v125, v4 offset:724
	ds_read_b32 v126, v4 offset:856
	ds_read_b32 v127, v4 offset:988
	s_waitcnt lgkmcnt(8)
	v_cvt_pk_bf16_f32 v140, v112, v113
	v_cvt_pk_bf16_f32 v141, v114, v115
	v_cvt_pk_bf16_f32 v142, v116, v117
	v_cvt_pk_bf16_f32 v143, v118, v119
	global_store_dwordx4 v6, v[140:143], s[32:33] nt
	s_add_u32 s32, s32, s49
	s_addc_u32 s33, s33, 0
	ds_read_b32 v128, v4 offset:96
	ds_read_b32 v129, v4 offset:228
	ds_read_b32 v130, v4 offset:360
	ds_read_b32 v131, v4 offset:492
	ds_read_b32 v132, v4 offset:624
	ds_read_b32 v133, v4 offset:756
	ds_read_b32 v134, v4 offset:888
	ds_read_b32 v135, v4 offset:1020
	s_waitcnt lgkmcnt(8)
	v_cvt_pk_bf16_f32 v136, v120, v121
	v_cvt_pk_bf16_f32 v137, v122, v123
	v_cvt_pk_bf16_f32 v138, v124, v125
	v_cvt_pk_bf16_f32 v139, v126, v127
	global_store_dwordx4 v6, v[136:139], s[32:33] nt
	s_add_u32 s32, s32, s49
	s_addc_u32 s33, s33, 0
	s_waitcnt lgkmcnt(0)
	v_cvt_pk_bf16_f32 v140, v128, v129
	v_cvt_pk_bf16_f32 v141, v130, v131
	v_cvt_pk_bf16_f32 v142, v132, v133
	v_cvt_pk_bf16_f32 v143, v134, v135
	global_store_dwordx4 v6, v[140:143], s[32:33] nt
	s_add_u32 s32, s32, s49
	s_addc_u32 s33, s33, 0
	s_cmp_ge_u32 s20, 10240
	s_cbranch_scc1 .Ltt7_0_dr3
	s_cmp_lt_u32 s20, 6144
	s_cbranch_scc1 .Ltt7_0_r4_s0
	s_sub_u32 s25, s20, 6144
	s_lshr_b32 s27, s25, 8
	s_and_b32 s31, s25, 255
	s_mul_i32 s35, s27, 0x200000
	s_lshl_b32 s41, s31, 7
	s_add_u32 s35, s35, s41
	s_add_u32 s0, s66, s35
	s_addc_u32 s1, s67, 0
	s_mul_i32 s35, s31, 0x20000
	s_lshl_b32 s41, s27, 7
	s_add_u32 s35, s35, s41
	s_add_u32 s2, s68, s35
	s_addc_u32 s3, s69, 0
	s_mov_b32 s5, 0x8000
	s_mov_b32 s6, 0x40000
	s_mov_b32 s7, 0x1000
	s_branch .Ltt7_0_r4_e

.Ltt7_0_loop:
	s_cmp_ge_u32 s20, 10240
	s_cbranch_scc1 .Ltt7_0_dr4
	s_cmp_lt_u32 s20, 6144
	s_cbranch_scc1 .Ltt7_0_r5_s0
	s_sub_u32 s25, s20, 6144
	s_lshr_b32 s27, s25, 8
	s_and_b32 s31, s25, 255
	s_mul_i32 s35, s27, 0x200000
	s_lshl_b32 s41, s31, 7
	s_add_u32 s35, s35, s41
	s_add_u32 s0, s66, s35
	s_addc_u32 s1, s67, 0
	s_mul_i32 s35, s31, 0x20000
	s_lshl_b32 s41, s27, 7
	s_add_u32 s35, s35, s41
	s_add_u32 s10, s68, s35
	s_addc_u32 s11, s69, 0
	s_mov_b32 s5, 0x8000
	s_mov_b32 s6, 0x40000
	s_mov_b32 s47, 0x1000
	s_branch .Ltt7_0_r5_e

.Ltt7_0_r5_e:
	v_mad_u32_u24 v5, v1, s5, v2
	global_load_dwordx4 v[40:43], v5, s[0:1] nt
	s_add_u32 s0, s0, s6
	s_addc_u32 s1, s1, 0
	global_load_dwordx4 v[44:47], v5, s[0:1] nt
	s_add_u32 s0, s0, s6
	s_addc_u32 s1, s1, 0
	global_load_dwordx4 v[48:51], v5, s[0:1] nt
	s_add_u32 s0, s0, s6
	s_addc_u32 s1, s1, 0
	global_load_dwordx4 v[52:55], v5, s[0:1] nt
	s_add_u32 s0, s0, s6
	s_addc_u32 s1, s1, 0
	global_load_dwordx4 v[56:59], v5, s[0:1] nt
	s_add_u32 s0, s0, s6
	s_addc_u32 s1, s1, 0
	global_load_dwordx4 v[60:63], v5, s[0:1] nt
	s_add_u32 s0, s0, s6
	s_addc_u32 s1, s1, 0
	global_load_dwordx4 v[64:67], v5, s[0:1] nt
	s_add_u32 s0, s0, s6
	s_addc_u32 s1, s1, 0
	global_load_dwordx4 v[68:71], v5, s[0:1] nt
	s_add_u32 s0, s0, s6
	s_addc_u32 s1, s1, 0
	s_add_u32 s20, s20, s23
	s_waitcnt vmcnt(24)
	ds_write_b32 v3, v72 offset:0
	ds_write_b32 v3, v73 offset:4
	ds_write_b32 v3, v74 offset:8
	ds_write_b32 v3, v75 offset:12
	ds_write_b32 v3, v76 offset:1056
	ds_write_b32 v3, v77 offset:1060
	ds_write_b32 v3, v78 offset:1064
	ds_write_b32 v3, v79 offset:1068
	ds_write_b32 v3, v80 offset:2112
	ds_write_b32 v3, v81 offset:2116
	ds_write_b32 v3, v82 offset:2120
	ds_write_b32 v3, v83 offset:2124
	ds_write_b32 v3, v84 offset:3168
	ds_write_b32 v3, v85 offset:3172
	ds_write_b32 v3, v86 offset:3176
	ds_write_b32 v3, v87 offset:3180
	ds_write_b32 v3, v88 offset:4224
	ds_write_b32 v3, v89 offset:4228
	ds_write_b32 v3, v90 offset:4232
	ds_write_b32 v3, v91 offset:4236
	ds_write_b32 v3, v92 offset:5280
	ds_write_b32 v3, v93 offset:5284
	ds_write_b32 v3, v94 offset:5288
	ds_write_b32 v3, v95 offset:5292
	ds_write_b32 v3, v96 offset:6336
	ds_write_b32 v3, v97 offset:6340
	ds_write_b32 v3, v98 offset:6344
	ds_write_b32 v3, v99 offset:6348
	ds_write_b32 v3, v100 offset:7392
	ds_write_b32 v3, v101 offset:7396
	ds_write_b32 v3, v102 offset:7400
	ds_write_b32 v3, v103 offset:7404
	s_mov_b32 s32, s42
	s_mov_b32 s33, s43
	s_lshl_b32 s49, s44, 3
	v_mad_u32_u24 v6, v1, s44, v2
	s_waitcnt lgkmcnt(0)
	ds_read_b32 v104, v4 offset:0
	ds_read_b32 v105, v4 offset:132
	ds_read_b32 v106, v4 offset:264
	ds_read_b32 v107, v4 offset:396
	ds_read_b32 v108, v4 offset:528
	ds_read_b32 v109, v4 offset:660
	ds_read_b32 v110, v4 offset:792
	ds_read_b32 v111, v4 offset:924
	ds_read_b32 v112, v4 offset:32
	ds_read_b32 v113, v4 offset:164
	ds_read_b32 v114, v4 offset:296
	ds_read_b32 v115, v4 offset:428
	ds_read_b32 v116, v4 offset:560
	ds_read_b32 v117, v4 offset:692
	ds_read_b32 v118, v4 offset:824
	ds_read_b32 v119, v4 offset:956
	s_waitcnt lgkmcnt(8)
	v_cvt_pk_bf16_f32 v136, v104, v105
	v_cvt_pk_bf16_f32 v137, v106, v107
	v_cvt_pk_bf16_f32 v138, v108, v109
	v_cvt_pk_bf16_f32 v139, v110, v111
	global_store_dwordx4 v6, v[136:139], s[32:33] nt
	s_add_u32 s32, s32, s49
	s_addc_u32 s33, s33, 0
	ds_read_b32 v120, v4 offset:64
	ds_read_b32 v121, v4 offset:196
	ds_read_b32 v122, v4 offset:328
	ds_read_b32 v123, v4 offset:460
	ds_read_b32 v124, v4 offset:592
	ds_read_b32 v125, v4 offset:724
	ds_read_b32 v126, v4 offset:856
	ds_read_b32 v127, v4 offset:988
	s_waitcnt lgkmcnt(8)
	v_cvt_pk_bf16_f32 v140, v112, v113
	v_cvt_pk_bf16_f32 v141, v114, v115
	v_cvt_pk_bf16_f32 v142, v116, v117
	v_cvt_pk_bf16_f32 v143, v118, v119
	global_store_dwordx4 v6, v[140:143], s[32:33] nt
	s_add_u32 s32, s32, s49
	s_addc_u32 s33, s33, 0
	ds_read_b32 v128, v4 offset:96
	ds_read_b32 v129, v4 offset:228
	ds_read_b32 v130, v4 offset:360
	ds_read_b32 v131, v4 offset:492
	ds_read_b32 v132, v4 offset:624
	ds_read_b32 v133, v4 offset:756
	ds_read_b32 v134, v4 offset:888
	ds_read_b32 v135, v4 offset:1020
	s_waitcnt lgkmcnt(8)
	v_cvt_pk_bf16_f32 v136, v120, v121
	v_cvt_pk_bf16_f32 v137, v122, v123
	v_cvt_pk_bf16_f32 v138, v124, v125
	v_cvt_pk_bf16_f32 v139, v126, v127
	global_store_dwordx4 v6, v[136:139], s[32:33] nt
	s_add_u32 s32, s32, s49
	s_addc_u32 s33, s33, 0
	s_waitcnt lgkmcnt(0)
	v_cvt_pk_bf16_f32 v140, v128, v129
	v_cvt_pk_bf16_f32 v141, v130, v131
	v_cvt_pk_bf16_f32 v142, v132, v133
	v_cvt_pk_bf16_f32 v143, v134, v135
	global_store_dwordx4 v6, v[140:143], s[32:33] nt
	s_add_u32 s32, s32, s49
	s_addc_u32 s33, s33, 0
	s_cmp_ge_u32 s20, 10240
	s_cbranch_scc1 .Ltt7_0_dr5
	s_cmp_lt_u32 s20, 6144
	s_cbranch_scc1 .Ltt7_0_r6_s0
	s_sub_u32 s25, s20, 6144
	s_lshr_b32 s27, s25, 8
	s_and_b32 s31, s25, 255
	s_mul_i32 s35, s27, 0x200000
	s_lshl_b32 s41, s31, 7
	s_add_u32 s35, s35, s41
	s_add_u32 s0, s66, s35
	s_addc_u32 s1, s67, 0
	s_mul_i32 s35, s31, 0x20000
	s_lshl_b32 s41, s27, 7
	s_add_u32 s35, s35, s41
	s_add_u32 s42, s68, s35
	s_addc_u32 s43, s69, 0
	s_mov_b32 s5, 0x8000
	s_mov_b32 s6, 0x40000
	s_mov_b32 s44, 0x1000
	s_branch .Ltt7_0_r6_e

.Ltt7_0_r6_e:
	v_mad_u32_u24 v5, v1, s5, v2
	global_load_dwordx4 v[72:75], v5, s[0:1] nt
	s_add_u32 s0, s0, s6
	s_addc_u32 s1, s1, 0
	global_load_dwordx4 v[76:79], v5, s[0:1] nt
	s_add_u32 s0, s0, s6
	s_addc_u32 s1, s1, 0
	global_load_dwordx4 v[80:83], v5, s[0:1] nt
	s_add_u32 s0, s0, s6
	s_addc_u32 s1, s1, 0
	global_load_dwordx4 v[84:87], v5, s[0:1] nt
	s_add_u32 s0, s0, s6
	s_addc_u32 s1, s1, 0
	global_load_dwordx4 v[88:91], v5, s[0:1] nt
	s_add_u32 s0, s0, s6
	s_addc_u32 s1, s1, 0
	global_load_dwordx4 v[92:95], v5, s[0:1] nt
	s_add_u32 s0, s0, s6
	s_addc_u32 s1, s1, 0
	global_load_dwordx4 v[96:99], v5, s[0:1] nt
	s_add_u32 s0, s0, s6
	s_addc_u32 s1, s1, 0
	global_load_dwordx4 v[100:103], v5, s[0:1] nt
	s_add_u32 s0, s0, s6
	s_addc_u32 s1, s1, 0
	s_add_u32 s20, s20, s23
	s_waitcnt vmcnt(24)
	ds_write_b32 v3, v8 offset:0
	ds_write_b32 v3, v9 offset:4
	ds_write_b32 v3, v10 offset:8
	ds_write_b32 v3, v11 offset:12
	ds_write_b32 v3, v12 offset:1056
	ds_write_b32 v3, v13 offset:1060
	ds_write_b32 v3, v14 offset:1064
	ds_write_b32 v3, v15 offset:1068
	ds_write_b32 v3, v16 offset:2112
	ds_write_b32 v3, v17 offset:2116
	ds_write_b32 v3, v18 offset:2120
	ds_write_b32 v3, v19 offset:2124
	ds_write_b32 v3, v20 offset:3168
	ds_write_b32 v3, v21 offset:3172
	ds_write_b32 v3, v22 offset:3176
	ds_write_b32 v3, v23 offset:3180
	ds_write_b32 v3, v24 offset:4224
	ds_write_b32 v3, v25 offset:4228
	ds_write_b32 v3, v26 offset:4232
	ds_write_b32 v3, v27 offset:4236
	ds_write_b32 v3, v28 offset:5280
	ds_write_b32 v3, v29 offset:5284
	ds_write_b32 v3, v30 offset:5288
	ds_write_b32 v3, v31 offset:5292
	ds_write_b32 v3, v32 offset:6336
	ds_write_b32 v3, v33 offset:6340
	ds_write_b32 v3, v34 offset:6344
	ds_write_b32 v3, v35 offset:6348
	ds_write_b32 v3, v36 offset:7392
	ds_write_b32 v3, v37 offset:7396
	ds_write_b32 v3, v38 offset:7400
	ds_write_b32 v3, v39 offset:7404
	s_mov_b32 s32, s2
	s_mov_b32 s33, s3
	s_lshl_b32 s49, s7, 3
	v_mad_u32_u24 v6, v1, s7, v2
	s_waitcnt lgkmcnt(0)
	ds_read_b32 v104, v4 offset:0
	ds_read_b32 v105, v4 offset:132
	ds_read_b32 v106, v4 offset:264
	ds_read_b32 v107, v4 offset:396
	ds_read_b32 v108, v4 offset:528
	ds_read_b32 v109, v4 offset:660
	ds_read_b32 v110, v4 offset:792
	ds_read_b32 v111, v4 offset:924
	ds_read_b32 v112, v4 offset:32
	ds_read_b32 v113, v4 offset:164
	ds_read_b32 v114, v4 offset:296
	ds_read_b32 v115, v4 offset:428
	ds_read_b32 v116, v4 offset:560
	ds_read_b32 v117, v4 offset:692
	ds_read_b32 v118, v4 offset:824
	ds_read_b32 v119, v4 offset:956
	s_waitcnt lgkmcnt(8)
	v_cvt_pk_bf16_f32 v136, v104, v105
	v_cvt_pk_bf16_f32 v137, v106, v107
	v_cvt_pk_bf16_f32 v138, v108, v109
	v_cvt_pk_bf16_f32 v139, v110, v111
	global_store_dwordx4 v6, v[136:139], s[32:33] nt
	s_add_u32 s32, s32, s49
	s_addc_u32 s33, s33, 0
	ds_read_b32 v120, v4 offset:64
	ds_read_b32 v121, v4 offset:196
	ds_read_b32 v122, v4 offset:328
	ds_read_b32 v123, v4 offset:460
	ds_read_b32 v124, v4 offset:592
	ds_read_b32 v125, v4 offset:724
	ds_read_b32 v126, v4 offset:856
	ds_read_b32 v127, v4 offset:988
	s_waitcnt lgkmcnt(8)
	v_cvt_pk_bf16_f32 v140, v112, v113
	v_cvt_pk_bf16_f32 v141, v114, v115
	v_cvt_pk_bf16_f32 v142, v116, v117
	v_cvt_pk_bf16_f32 v143, v118, v119
	global_store_dwordx4 v6, v[140:143], s[32:33] nt
	s_add_u32 s32, s32, s49
	s_addc_u32 s33, s33, 0
	ds_read_b32 v128, v4 offset:96
	ds_read_b32 v129, v4 offset:228
	ds_read_b32 v130, v4 offset:360
	ds_read_b32 v131, v4 offset:492
	ds_read_b32 v132, v4 offset:624
	ds_read_b32 v133, v4 offset:756
	ds_read_b32 v134, v4 offset:888
	ds_read_b32 v135, v4 offset:1020
	s_waitcnt lgkmcnt(8)
	v_cvt_pk_bf16_f32 v136, v120, v121
	v_cvt_pk_bf16_f32 v137, v122, v123
	v_cvt_pk_bf16_f32 v138, v124, v125
	v_cvt_pk_bf16_f32 v139, v126, v127
	global_store_dwordx4 v6, v[136:139], s[32:33] nt
	s_add_u32 s32, s32, s49
	s_addc_u32 s33, s33, 0
	s_waitcnt lgkmcnt(0)
	v_cvt_pk_bf16_f32 v140, v128, v129
	v_cvt_pk_bf16_f32 v141, v130, v131
	v_cvt_pk_bf16_f32 v142, v132, v133
	v_cvt_pk_bf16_f32 v143, v134, v135
	global_store_dwordx4 v6, v[140:143], s[32:33] nt
	s_add_u32 s32, s32, s49
	s_addc_u32 s33, s33, 0
	s_cmp_ge_u32 s20, 10240
	s_cbranch_scc1 .Ltt7_0_dr6
	s_cmp_lt_u32 s20, 6144
	s_cbranch_scc1 .Ltt7_0_r7_s0
	s_sub_u32 s25, s20, 6144
	s_lshr_b32 s27, s25, 8
	s_and_b32 s31, s25, 255
	s_mul_i32 s35, s27, 0x200000
	s_lshl_b32 s41, s31, 7
	s_add_u32 s35, s35, s41
	s_add_u32 s0, s66, s35
	s_addc_u32 s1, s67, 0
	s_mul_i32 s35, s31, 0x20000
	s_lshl_b32 s41, s27, 7
	s_add_u32 s35, s35, s41
	s_add_u32 s2, s68, s35
	s_addc_u32 s3, s69, 0
	s_mov_b32 s5, 0x8000
	s_mov_b32 s6, 0x40000
	s_mov_b32 s7, 0x1000
	s_branch .Ltt7_0_r7_e

.LBB0_1154:
	s_waitcnt vmcnt(0)
	s_barrier
	s_cmp_lg_u32 s87, 0x100
	s_cbranch_scc1 .Ltt10_0_done
	s_cmp_lt_u32 s96, 96
	s_cbranch_scc1 .Ltt10_0_done
	s_cmp_ge_u32 s96, 256
	s_cbranch_scc1 .Ltt10_0_done
	s_sub_u32 s20, s96, 96
	s_lshl_b32 s20, s20, 3
	s_add_u32 s20, s20, s93
	s_movk_i32 s23, 1280
	v_mbcnt_hi_u32_b32 v0, -1, v212
	v_and_b32_e32 v0, 63, v0
	v_lshrrev_b32_e32 v1, 3, v0
	v_and_b32_e32 v2, 7, v0
	s_lshl_b32 s25, s93, 14
	v_mul_u32_u24_e32 v3, 0x84, v1
	v_mul_u32_u24_e32 v4, 0x420, v2
	v_lshlrev_b32_e32 v2, 4, v2
	v_add3_u32 v3, v3, v2, s25
	v_lshl_add_u32 v4, v1, 2, v4
	v_add_u32_e32 v4, s25, v4
	v_and_b32_e32 v7, 4, v1
	v_and_b32_e32 v5, 3, v1
	v_lshl_add_u32 v7, v7, 1, v5
	v_readlane_b32 s62, v245, 0
	v_readlane_b32 s63, v245, 1
	s_add_u32 s64, s76, 0x6989000
	s_addc_u32 s65, s77, 0
	s_nop 0
	s_add_u32 s62, s62, 0x4000000
	s_addc_u32 s63, s63, 0
	v_readlane_b32 s66, v244, 21
	v_readlane_b32 s67, v244, 22
	s_add_u32 s68, s76, 0xa989000
	s_addc_u32 s69, s77, 0
	s_nop 0
	s_add_u32 s66, s66, 0x4000000
	s_addc_u32 s67, s67, 0
	s_cmp_ge_u32 s20, 12288
	s_cbranch_scc1 .Ltt10_0_done
	s_cmp_lt_u32 s20, 4096
	s_cbranch_scc1 .Ltt10_0_r1_s0
	s_sub_u32 s25, s20, 4096
	s_lshr_b32 s27, s25, 6
	s_and_b32 s31, s25, 63
	s_mul_i32 s35, s27, 0x80000
	s_lshl_b32 s41, s31, 7
	s_add_u32 s35, s35, s41
	s_add_u32 s0, s66, s35
	s_addc_u32 s1, s67, 0
	s_mul_i32 s35, s31, 0x80000
	s_lshl_b32 s41, s27, 7
	s_add_u32 s35, s35, s41
	s_add_u32 s2, s68, s35
	s_addc_u32 s3, s69, 0
	s_mov_b32 s5, 0x2000
	s_mov_b32 s6, 0x10000
	s_mov_b32 s7, 0x4000
	s_branch .Ltt10_0_r1_e
.Ltt10_0_r1_s0:
	s_sub_u32 s25, s20, -4096
	s_lshr_b32 s27, s25, 8
	s_and_b32 s31, s25, 255
	s_mul_i32 s35, s27, 0x200000
	s_lshl_b32 s41, s31, 7
	s_add_u32 s35, s35, s41
	s_add_u32 s0, s62, s35
	s_addc_u32 s1, s63, 0
	s_mul_i32 s35, s31, 0x20000
	s_lshl_b32 s41, s27, 7
	s_add_u32 s35, s35, s41
	s_add_u32 s2, s64, s35
	s_addc_u32 s3, s65, 0
	s_mov_b32 s5, 0x8000
	s_mov_b32 s6, 0x40000
	s_mov_b32 s7, 0x1000
.Ltt10_0_r1_e:
	v_mad_u32_u24 v5, v1, s5, v2
	global_load_dwordx4 v[8:11], v5, s[0:1] nt
	s_add_u32 s0, s0, s6
	s_addc_u32 s1, s1, 0
	global_load_dwordx4 v[12:15], v5, s[0:1] nt
	s_add_u32 s0, s0, s6
	s_addc_u32 s1, s1, 0
	global_load_dwordx4 v[16:19], v5, s[0:1] nt
	s_add_u32 s0, s0, s6
	s_addc_u32 s1, s1, 0
	global_load_dwordx4 v[20:23], v5, s[0:1] nt
	s_add_u32 s0, s0, s6
	s_addc_u32 s1, s1, 0
	global_load_dwordx4 v[24:27], v5, s[0:1] nt
	s_add_u32 s0, s0, s6
	s_addc_u32 s1, s1, 0
	global_load_dwordx4 v[28:31], v5, s[0:1] nt
	s_add_u32 s0, s0, s6
	s_addc_u32 s1, s1, 0
	global_load_dwordx4 v[32:35], v5, s[0:1] nt
	s_add_u32 s0, s0, s6
	s_addc_u32 s1, s1, 0
	global_load_dwordx4 v[36:39], v5, s[0:1] nt
	s_add_u32 s0, s0, s6
	s_addc_u32 s1, s1, 0
	s_add_u32 s20, s20, s23
	s_cmp_ge_u32 s20, 12288
	s_cbranch_scc1 .Ltt10_0_dr1
	s_cmp_lt_u32 s20, 4096
	s_cbranch_scc1 .Ltt10_0_r2_s0
	s_sub_u32 s25, s20, 4096
	s_lshr_b32 s27, s25, 6
	s_and_b32 s31, s25, 63
	s_mul_i32 s35, s27, 0x80000
	s_lshl_b32 s41, s31, 7
	s_add_u32 s35, s35, s41
	s_add_u32 s0, s66, s35
	s_addc_u32 s1, s67, 0
	s_mul_i32 s35, s31, 0x80000
	s_lshl_b32 s41, s27, 7
	s_add_u32 s35, s35, s41
	s_add_u32 s10, s68, s35
	s_addc_u32 s11, s69, 0
	s_mov_b32 s5, 0x2000
	s_mov_b32 s6, 0x10000
	s_mov_b32 s47, 0x4000
	s_branch .Ltt10_0_r2_e
.Ltt10_0_r2_s0:
	s_sub_u32 s25, s20, -4096
	s_lshr_b32 s27, s25, 8
	s_and_b32 s31, s25, 255
	s_mul_i32 s35, s27, 0x200000
	s_lshl_b32 s41, s31, 7
	s_add_u32 s35, s35, s41
	s_add_u32 s0, s62, s35
	s_addc_u32 s1, s63, 0
	s_mul_i32 s35, s31, 0x20000
	s_lshl_b32 s41, s27, 7
	s_add_u32 s35, s35, s41
	s_add_u32 s10, s64, s35
	s_addc_u32 s11, s65, 0
	s_mov_b32 s5, 0x8000
	s_mov_b32 s6, 0x40000
	s_mov_b32 s47, 0x1000
.Ltt10_0_r2_e:
	v_mad_u32_u24 v5, v1, s5, v2
	global_load_dwordx4 v[40:43], v5, s[0:1] nt
	s_add_u32 s0, s0, s6
	s_addc_u32 s1, s1, 0
	global_load_dwordx4 v[44:47], v5, s[0:1] nt
	s_add_u32 s0, s0, s6
	s_addc_u32 s1, s1, 0
	global_load_dwordx4 v[48:51], v5, s[0:1] nt
	s_add_u32 s0, s0, s6
	s_addc_u32 s1, s1, 0
	global_load_dwordx4 v[52:55], v5, s[0:1] nt
	s_add_u32 s0, s0, s6
	s_addc_u32 s1, s1, 0
	global_load_dwordx4 v[56:59], v5, s[0:1] nt
	s_add_u32 s0, s0, s6
	s_addc_u32 s1, s1, 0
	global_load_dwordx4 v[60:63], v5, s[0:1] nt
	s_add_u32 s0, s0, s6
	s_addc_u32 s1, s1, 0
	global_load_dwordx4 v[64:67], v5, s[0:1] nt
	s_add_u32 s0, s0, s6
	s_addc_u32 s1, s1, 0
	global_load_dwordx4 v[68:71], v5, s[0:1] nt
	s_add_u32 s0, s0, s6
	s_addc_u32 s1, s1, 0
	s_add_u32 s20, s20, s23
	s_cmp_ge_u32 s20, 12288
	s_cbranch_scc1 .Ltt10_0_dr2
	s_cmp_lt_u32 s20, 4096
	s_cbranch_scc1 .Ltt10_0_r3_s0
	s_sub_u32 s25, s20, 4096
	s_lshr_b32 s27, s25, 6
	s_and_b32 s31, s25, 63
	s_mul_i32 s35, s27, 0x80000
	s_lshl_b32 s41, s31, 7
	s_add_u32 s35, s35, s41
	s_add_u32 s0, s66, s35
	s_addc_u32 s1, s67, 0
	s_mul_i32 s35, s31, 0x80000
	s_lshl_b32 s41, s27, 7
	s_add_u32 s35, s35, s41
	s_add_u32 s42, s68, s35
	s_addc_u32 s43, s69, 0
	s_mov_b32 s5, 0x2000
	s_mov_b32 s6, 0x10000
	s_mov_b32 s44, 0x4000
	s_branch .Ltt10_0_r3_e
.Ltt10_0_r3_s0:
	s_sub_u32 s25, s20, -4096
	s_lshr_b32 s27, s25, 8
	s_and_b32 s31, s25, 255
	s_mul_i32 s35, s27, 0x200000
	s_lshl_b32 s41, s31, 7
	s_add_u32 s35, s35, s41
	s_add_u32 s0, s62, s35
	s_addc_u32 s1, s63, 0
	s_mul_i32 s35, s31, 0x20000
	s_lshl_b32 s41, s27, 7
	s_add_u32 s35, s35, s41
	s_add_u32 s42, s64, s35
	s_addc_u32 s43, s65, 0
	s_mov_b32 s5, 0x8000
	s_mov_b32 s6, 0x40000
	s_mov_b32 s44, 0x1000
.Ltt10_0_r3_e:
	v_mad_u32_u24 v5, v1, s5, v2
	global_load_dwordx4 v[72:75], v5, s[0:1] nt
	s_add_u32 s0, s0, s6
	s_addc_u32 s1, s1, 0
	global_load_dwordx4 v[76:79], v5, s[0:1] nt
	s_add_u32 s0, s0, s6
	s_addc_u32 s1, s1, 0
	global_load_dwordx4 v[80:83], v5, s[0:1] nt
	s_add_u32 s0, s0, s6
	s_addc_u32 s1, s1, 0
	global_load_dwordx4 v[84:87], v5, s[0:1] nt
	s_add_u32 s0, s0, s6
	s_addc_u32 s1, s1, 0
	global_load_dwordx4 v[88:91], v5, s[0:1] nt
	s_add_u32 s0, s0, s6
	s_addc_u32 s1, s1, 0
	global_load_dwordx4 v[92:95], v5, s[0:1] nt
	s_add_u32 s0, s0, s6
	s_addc_u32 s1, s1, 0
	global_load_dwordx4 v[96:99], v5, s[0:1] nt
	s_add_u32 s0, s0, s6
	s_addc_u32 s1, s1, 0
	global_load_dwordx4 v[100:103], v5, s[0:1] nt
	s_add_u32 s0, s0, s6
	s_addc_u32 s1, s1, 0
	s_add_u32 s20, s20, s23
	s_waitcnt vmcnt(16)
	ds_write_b32 v3, v8 offset:0
	ds_write_b32 v3, v9 offset:4
	ds_write_b32 v3, v10 offset:8
	ds_write_b32 v3, v11 offset:12
	ds_write_b32 v3, v12 offset:1056
	ds_write_b32 v3, v13 offset:1060
	ds_write_b32 v3, v14 offset:1064
	ds_write_b32 v3, v15 offset:1068
	ds_write_b32 v3, v16 offset:2112
	ds_write_b32 v3, v17 offset:2116
	ds_write_b32 v3, v18 offset:2120
	ds_write_b32 v3, v19 offset:2124
	ds_write_b32 v3, v20 offset:3168
	ds_write_b32 v3, v21 offset:3172
	ds_write_b32 v3, v22 offset:3176
	ds_write_b32 v3, v23 offset:3180
	ds_write_b32 v3, v24 offset:4224
	ds_write_b32 v3, v25 offset:4228
	ds_write_b32 v3, v26 offset:4232
	ds_write_b32 v3, v27 offset:4236
	ds_write_b32 v3, v28 offset:5280
	ds_write_b32 v3, v29 offset:5284
	ds_write_b32 v3, v30 offset:5288
	ds_write_b32 v3, v31 offset:5292
	ds_write_b32 v3, v32 offset:6336
	ds_write_b32 v3, v33 offset:6340
	ds_write_b32 v3, v34 offset:6344
	ds_write_b32 v3, v35 offset:6348
	ds_write_b32 v3, v36 offset:7392
	ds_write_b32 v3, v37 offset:7396
	ds_write_b32 v3, v38 offset:7400
	ds_write_b32 v3, v39 offset:7404
	s_mov_b32 s32, s2
	s_mov_b32 s33, s3
	s_lshl_b32 s49, s7, 3
	v_mad_u32_u24 v6, v1, s7, v2
	s_waitcnt lgkmcnt(0)
	ds_read_b32 v104, v4 offset:0
	ds_read_b32 v105, v4 offset:132
	ds_read_b32 v106, v4 offset:264
	ds_read_b32 v107, v4 offset:396
	ds_read_b32 v108, v4 offset:528
	ds_read_b32 v109, v4 offset:660
	ds_read_b32 v110, v4 offset:792
	ds_read_b32 v111, v4 offset:924
	ds_read_b32 v112, v4 offset:32
	ds_read_b32 v113, v4 offset:164
	ds_read_b32 v114, v4 offset:296
	ds_read_b32 v115, v4 offset:428
	ds_read_b32 v116, v4 offset:560
	ds_read_b32 v117, v4 offset:692
	ds_read_b32 v118, v4 offset:824
	ds_read_b32 v119, v4 offset:956
	s_waitcnt lgkmcnt(8)
	v_cvt_pk_bf16_f32 v136, v104, v105
	v_cvt_pk_bf16_f32 v137, v106, v107
	v_cvt_pk_bf16_f32 v138, v108, v109
	v_cvt_pk_bf16_f32 v139, v110, v111
	global_store_dwordx4 v6, v[136:139], s[32:33] nt
	s_add_u32 s32, s32, s49
	s_addc_u32 s33, s33, 0
	ds_read_b32 v120, v4 offset:64
	ds_read_b32 v121, v4 offset:196
	ds_read_b32 v122, v4 offset:328
	ds_read_b32 v123, v4 offset:460
	ds_read_b32 v124, v4 offset:592
	ds_read_b32 v125, v4 offset:724
	ds_read_b32 v126, v4 offset:856
	ds_read_b32 v127, v4 offset:988
	s_waitcnt lgkmcnt(8)
	v_cvt_pk_bf16_f32 v140, v112, v113
	v_cvt_pk_bf16_f32 v141, v114, v115
	v_cvt_pk_bf16_f32 v142, v116, v117
	v_cvt_pk_bf16_f32 v143, v118, v119
	global_store_dwordx4 v6, v[140:143], s[32:33] nt
	s_add_u32 s32, s32, s49
	s_addc_u32 s33, s33, 0
	ds_read_b32 v128, v4 offset:96
	ds_read_b32 v129, v4 offset:228
	ds_read_b32 v130, v4 offset:360
	ds_read_b32 v131, v4 offset:492
	ds_read_b32 v132, v4 offset:624
	ds_read_b32 v133, v4 offset:756
	ds_read_b32 v134, v4 offset:888
	ds_read_b32 v135, v4 offset:1020
	s_waitcnt lgkmcnt(8)
	v_cvt_pk_bf16_f32 v136, v120, v121
	v_cvt_pk_bf16_f32 v137, v122, v123
	v_cvt_pk_bf16_f32 v138, v124, v125
	v_cvt_pk_bf16_f32 v139, v126, v127
	global_store_dwordx4 v6, v[136:139], s[32:33] nt
	s_add_u32 s32, s32, s49
	s_addc_u32 s33, s33, 0
	s_waitcnt lgkmcnt(0)
	v_cvt_pk_bf16_f32 v140, v128, v129
	v_cvt_pk_bf16_f32 v141, v130, v131
	v_cvt_pk_bf16_f32 v142, v132, v133
	v_cvt_pk_bf16_f32 v143, v134, v135
	global_store_dwordx4 v6, v[140:143], s[32:33] nt
	s_add_u32 s32, s32, s49
	s_addc_u32 s33, s33, 0
	s_cmp_ge_u32 s20, 12288
	s_cbranch_scc1 .Ltt10_0_dr3
	s_cmp_lt_u32 s20, 4096
	s_cbranch_scc1 .Ltt10_0_r4_s0
	s_sub_u32 s25, s20, 4096
	s_lshr_b32 s27, s25, 6
	s_and_b32 s31, s25, 63
	s_mul_i32 s35, s27, 0x80000
	s_lshl_b32 s41, s31, 7
	s_add_u32 s35, s35, s41
	s_add_u32 s0, s66, s35
	s_addc_u32 s1, s67, 0
	s_mul_i32 s35, s31, 0x80000
	s_lshl_b32 s41, s27, 7
	s_add_u32 s35, s35, s41
	s_add_u32 s2, s68, s35
	s_addc_u32 s3, s69, 0
	s_mov_b32 s5, 0x2000
	s_mov_b32 s6, 0x10000
	s_mov_b32 s7, 0x4000
	s_branch .Ltt10_0_r4_e

.Ltt10_0_loop:
	s_cmp_ge_u32 s20, 12288
	s_cbranch_scc1 .Ltt10_0_dr4
	s_cmp_lt_u32 s20, 4096
	s_cbranch_scc1 .Ltt10_0_r5_s0
	s_sub_u32 s25, s20, 4096
	s_lshr_b32 s27, s25, 6
	s_and_b32 s31, s25, 63
	s_mul_i32 s35, s27, 0x80000
	s_lshl_b32 s41, s31, 7
	s_add_u32 s35, s35, s41
	s_add_u32 s0, s66, s35
	s_addc_u32 s1, s67, 0
	s_mul_i32 s35, s31, 0x80000
	s_lshl_b32 s41, s27, 7
	s_add_u32 s35, s35, s41
	s_add_u32 s10, s68, s35
	s_addc_u32 s11, s69, 0
	s_mov_b32 s5, 0x2000
	s_mov_b32 s6, 0x10000
	s_mov_b32 s47, 0x4000
	s_branch .Ltt10_0_r5_e

.Ltt10_0_r5_e:
	v_mad_u32_u24 v5, v1, s5, v2
	global_load_dwordx4 v[40:43], v5, s[0:1] nt
	s_add_u32 s0, s0, s6
	s_addc_u32 s1, s1, 0
	global_load_dwordx4 v[44:47], v5, s[0:1] nt
	s_add_u32 s0, s0, s6
	s_addc_u32 s1, s1, 0
	global_load_dwordx4 v[48:51], v5, s[0:1] nt
	s_add_u32 s0, s0, s6
	s_addc_u32 s1, s1, 0
	global_load_dwordx4 v[52:55], v5, s[0:1] nt
	s_add_u32 s0, s0, s6
	s_addc_u32 s1, s1, 0
	global_load_dwordx4 v[56:59], v5, s[0:1] nt
	s_add_u32 s0, s0, s6
	s_addc_u32 s1, s1, 0
	global_load_dwordx4 v[60:63], v5, s[0:1] nt
	s_add_u32 s0, s0, s6
	s_addc_u32 s1, s1, 0
	global_load_dwordx4 v[64:67], v5, s[0:1] nt
	s_add_u32 s0, s0, s6
	s_addc_u32 s1, s1, 0
	global_load_dwordx4 v[68:71], v5, s[0:1] nt
	s_add_u32 s0, s0, s6
	s_addc_u32 s1, s1, 0
	s_add_u32 s20, s20, s23
	s_waitcnt vmcnt(24)
	ds_write_b32 v3, v72 offset:0
	ds_write_b32 v3, v73 offset:4
	ds_write_b32 v3, v74 offset:8
	ds_write_b32 v3, v75 offset:12
	ds_write_b32 v3, v76 offset:1056
	ds_write_b32 v3, v77 offset:1060
	ds_write_b32 v3, v78 offset:1064
	ds_write_b32 v3, v79 offset:1068
	ds_write_b32 v3, v80 offset:2112
	ds_write_b32 v3, v81 offset:2116
	ds_write_b32 v3, v82 offset:2120
	ds_write_b32 v3, v83 offset:2124
	ds_write_b32 v3, v84 offset:3168
	ds_write_b32 v3, v85 offset:3172
	ds_write_b32 v3, v86 offset:3176
	ds_write_b32 v3, v87 offset:3180
	ds_write_b32 v3, v88 offset:4224
	ds_write_b32 v3, v89 offset:4228
	ds_write_b32 v3, v90 offset:4232
	ds_write_b32 v3, v91 offset:4236
	ds_write_b32 v3, v92 offset:5280
	ds_write_b32 v3, v93 offset:5284
	ds_write_b32 v3, v94 offset:5288
	ds_write_b32 v3, v95 offset:5292
	ds_write_b32 v3, v96 offset:6336
	ds_write_b32 v3, v97 offset:6340
	ds_write_b32 v3, v98 offset:6344
	ds_write_b32 v3, v99 offset:6348
	ds_write_b32 v3, v100 offset:7392
	ds_write_b32 v3, v101 offset:7396
	ds_write_b32 v3, v102 offset:7400
	ds_write_b32 v3, v103 offset:7404
	s_mov_b32 s32, s42
	s_mov_b32 s33, s43
	s_lshl_b32 s49, s44, 3
	v_mad_u32_u24 v6, v1, s44, v2
	s_waitcnt lgkmcnt(0)
	ds_read_b32 v104, v4 offset:0
	ds_read_b32 v105, v4 offset:132
	ds_read_b32 v106, v4 offset:264
	ds_read_b32 v107, v4 offset:396
	ds_read_b32 v108, v4 offset:528
	ds_read_b32 v109, v4 offset:660
	ds_read_b32 v110, v4 offset:792
	ds_read_b32 v111, v4 offset:924
	ds_read_b32 v112, v4 offset:32
	ds_read_b32 v113, v4 offset:164
	ds_read_b32 v114, v4 offset:296
	ds_read_b32 v115, v4 offset:428
	ds_read_b32 v116, v4 offset:560
	ds_read_b32 v117, v4 offset:692
	ds_read_b32 v118, v4 offset:824
	ds_read_b32 v119, v4 offset:956
	s_waitcnt lgkmcnt(8)
	v_cvt_pk_bf16_f32 v136, v104, v105
	v_cvt_pk_bf16_f32 v137, v106, v107
	v_cvt_pk_bf16_f32 v138, v108, v109
	v_cvt_pk_bf16_f32 v139, v110, v111
	global_store_dwordx4 v6, v[136:139], s[32:33] nt
	s_add_u32 s32, s32, s49
	s_addc_u32 s33, s33, 0
	ds_read_b32 v120, v4 offset:64
	ds_read_b32 v121, v4 offset:196
	ds_read_b32 v122, v4 offset:328
	ds_read_b32 v123, v4 offset:460
	ds_read_b32 v124, v4 offset:592
	ds_read_b32 v125, v4 offset:724
	ds_read_b32 v126, v4 offset:856
	ds_read_b32 v127, v4 offset:988
	s_waitcnt lgkmcnt(8)
	v_cvt_pk_bf16_f32 v140, v112, v113
	v_cvt_pk_bf16_f32 v141, v114, v115
	v_cvt_pk_bf16_f32 v142, v116, v117
	v_cvt_pk_bf16_f32 v143, v118, v119
	global_store_dwordx4 v6, v[140:143], s[32:33] nt
	s_add_u32 s32, s32, s49
	s_addc_u32 s33, s33, 0
	ds_read_b32 v128, v4 offset:96
	ds_read_b32 v129, v4 offset:228
	ds_read_b32 v130, v4 offset:360
	ds_read_b32 v131, v4 offset:492
	ds_read_b32 v132, v4 offset:624
	ds_read_b32 v133, v4 offset:756
	ds_read_b32 v134, v4 offset:888
	ds_read_b32 v135, v4 offset:1020
	s_waitcnt lgkmcnt(8)
	v_cvt_pk_bf16_f32 v136, v120, v121
	v_cvt_pk_bf16_f32 v137, v122, v123
	v_cvt_pk_bf16_f32 v138, v124, v125
	v_cvt_pk_bf16_f32 v139, v126, v127
	global_store_dwordx4 v6, v[136:139], s[32:33] nt
	s_add_u32 s32, s32, s49
	s_addc_u32 s33, s33, 0
	s_waitcnt lgkmcnt(0)
	v_cvt_pk_bf16_f32 v140, v128, v129
	v_cvt_pk_bf16_f32 v141, v130, v131
	v_cvt_pk_bf16_f32 v142, v132, v133
	v_cvt_pk_bf16_f32 v143, v134, v135
	global_store_dwordx4 v6, v[140:143], s[32:33] nt
	s_add_u32 s32, s32, s49
	s_addc_u32 s33, s33, 0
	s_cmp_ge_u32 s20, 12288
	s_cbranch_scc1 .Ltt10_0_dr5
	s_cmp_lt_u32 s20, 4096
	s_cbranch_scc1 .Ltt10_0_r6_s0
	s_sub_u32 s25, s20, 4096
	s_lshr_b32 s27, s25, 6
	s_and_b32 s31, s25, 63
	s_mul_i32 s35, s27, 0x80000
	s_lshl_b32 s41, s31, 7
	s_add_u32 s35, s35, s41
	s_add_u32 s0, s66, s35
	s_addc_u32 s1, s67, 0
	s_mul_i32 s35, s31, 0x80000
	s_lshl_b32 s41, s27, 7
	s_add_u32 s35, s35, s41
	s_add_u32 s42, s68, s35
	s_addc_u32 s43, s69, 0
	s_mov_b32 s5, 0x2000
	s_mov_b32 s6, 0x10000
	s_mov_b32 s44, 0x4000
	s_branch .Ltt10_0_r6_e

.Ltt10_0_r6_e:
	v_mad_u32_u24 v5, v1, s5, v2
	global_load_dwordx4 v[72:75], v5, s[0:1] nt
	s_add_u32 s0, s0, s6
	s_addc_u32 s1, s1, 0
	global_load_dwordx4 v[76:79], v5, s[0:1] nt
	s_add_u32 s0, s0, s6
	s_addc_u32 s1, s1, 0
	global_load_dwordx4 v[80:83], v5, s[0:1] nt
	s_add_u32 s0, s0, s6
	s_addc_u32 s1, s1, 0
	global_load_dwordx4 v[84:87], v5, s[0:1] nt
	s_add_u32 s0, s0, s6
	s_addc_u32 s1, s1, 0
	global_load_dwordx4 v[88:91], v5, s[0:1] nt
	s_add_u32 s0, s0, s6
	s_addc_u32 s1, s1, 0
	global_load_dwordx4 v[92:95], v5, s[0:1] nt
	s_add_u32 s0, s0, s6
	s_addc_u32 s1, s1, 0
	global_load_dwordx4 v[96:99], v5, s[0:1] nt
	s_add_u32 s0, s0, s6
	s_addc_u32 s1, s1, 0
	global_load_dwordx4 v[100:103], v5, s[0:1] nt
	s_add_u32 s0, s0, s6
	s_addc_u32 s1, s1, 0
	s_add_u32 s20, s20, s23
	s_waitcnt vmcnt(24)
	ds_write_b32 v3, v8 offset:0
	ds_write_b32 v3, v9 offset:4
	ds_write_b32 v3, v10 offset:8
	ds_write_b32 v3, v11 offset:12
	ds_write_b32 v3, v12 offset:1056
	ds_write_b32 v3, v13 offset:1060
	ds_write_b32 v3, v14 offset:1064
	ds_write_b32 v3, v15 offset:1068
	ds_write_b32 v3, v16 offset:2112
	ds_write_b32 v3, v17 offset:2116
	ds_write_b32 v3, v18 offset:2120
	ds_write_b32 v3, v19 offset:2124
	ds_write_b32 v3, v20 offset:3168
	ds_write_b32 v3, v21 offset:3172
	ds_write_b32 v3, v22 offset:3176
	ds_write_b32 v3, v23 offset:3180
	ds_write_b32 v3, v24 offset:4224
	ds_write_b32 v3, v25 offset:4228
	ds_write_b32 v3, v26 offset:4232
	ds_write_b32 v3, v27 offset:4236
	ds_write_b32 v3, v28 offset:5280
	ds_write_b32 v3, v29 offset:5284
	ds_write_b32 v3, v30 offset:5288
	ds_write_b32 v3, v31 offset:5292
	ds_write_b32 v3, v32 offset:6336
	ds_write_b32 v3, v33 offset:6340
	ds_write_b32 v3, v34 offset:6344
	ds_write_b32 v3, v35 offset:6348
	ds_write_b32 v3, v36 offset:7392
	ds_write_b32 v3, v37 offset:7396
	ds_write_b32 v3, v38 offset:7400
	ds_write_b32 v3, v39 offset:7404
	s_mov_b32 s32, s2
	s_mov_b32 s33, s3
	s_lshl_b32 s49, s7, 3
	v_mad_u32_u24 v6, v1, s7, v2
	s_waitcnt lgkmcnt(0)
	ds_read_b32 v104, v4 offset:0
	ds_read_b32 v105, v4 offset:132
	ds_read_b32 v106, v4 offset:264
	ds_read_b32 v107, v4 offset:396
	ds_read_b32 v108, v4 offset:528
	ds_read_b32 v109, v4 offset:660
	ds_read_b32 v110, v4 offset:792
	ds_read_b32 v111, v4 offset:924
	ds_read_b32 v112, v4 offset:32
	ds_read_b32 v113, v4 offset:164
	ds_read_b32 v114, v4 offset:296
	ds_read_b32 v115, v4 offset:428
	ds_read_b32 v116, v4 offset:560
	ds_read_b32 v117, v4 offset:692
	ds_read_b32 v118, v4 offset:824
	ds_read_b32 v119, v4 offset:956
	s_waitcnt lgkmcnt(8)
	v_cvt_pk_bf16_f32 v136, v104, v105
	v_cvt_pk_bf16_f32 v137, v106, v107
	v_cvt_pk_bf16_f32 v138, v108, v109
	v_cvt_pk_bf16_f32 v139, v110, v111
	global_store_dwordx4 v6, v[136:139], s[32:33] nt
	s_add_u32 s32, s32, s49
	s_addc_u32 s33, s33, 0
	ds_read_b32 v120, v4 offset:64
	ds_read_b32 v121, v4 offset:196
	ds_read_b32 v122, v4 offset:328
	ds_read_b32 v123, v4 offset:460
	ds_read_b32 v124, v4 offset:592
	ds_read_b32 v125, v4 offset:724
	ds_read_b32 v126, v4 offset:856
	ds_read_b32 v127, v4 offset:988
	s_waitcnt lgkmcnt(8)
	v_cvt_pk_bf16_f32 v140, v112, v113
	v_cvt_pk_bf16_f32 v141, v114, v115
	v_cvt_pk_bf16_f32 v142, v116, v117
	v_cvt_pk_bf16_f32 v143, v118, v119
	global_store_dwordx4 v6, v[140:143], s[32:33] nt
	s_add_u32 s32, s32, s49
	s_addc_u32 s33, s33, 0
	ds_read_b32 v128, v4 offset:96
	ds_read_b32 v129, v4 offset:228
	ds_read_b32 v130, v4 offset:360
	ds_read_b32 v131, v4 offset:492
	ds_read_b32 v132, v4 offset:624
	ds_read_b32 v133, v4 offset:756
	ds_read_b32 v134, v4 offset:888
	ds_read_b32 v135, v4 offset:1020
	s_waitcnt lgkmcnt(8)
	v_cvt_pk_bf16_f32 v136, v120, v121
	v_cvt_pk_bf16_f32 v137, v122, v123
	v_cvt_pk_bf16_f32 v138, v124, v125
	v_cvt_pk_bf16_f32 v139, v126, v127
	global_store_dwordx4 v6, v[136:139], s[32:33] nt
	s_add_u32 s32, s32, s49
	s_addc_u32 s33, s33, 0
	s_waitcnt lgkmcnt(0)
	v_cvt_pk_bf16_f32 v140, v128, v129
	v_cvt_pk_bf16_f32 v141, v130, v131
	v_cvt_pk_bf16_f32 v142, v132, v133
	v_cvt_pk_bf16_f32 v143, v134, v135
	global_store_dwordx4 v6, v[140:143], s[32:33] nt
	s_add_u32 s32, s32, s49
	s_addc_u32 s33, s33, 0
	s_cmp_ge_u32 s20, 12288
	s_cbranch_scc1 .Ltt10_0_dr6
	s_cmp_lt_u32 s20, 4096
	s_cbranch_scc1 .Ltt10_0_r7_s0
	s_sub_u32 s25, s20, 4096
	s_lshr_b32 s27, s25, 6
	s_and_b32 s31, s25, 63
	s_mul_i32 s35, s27, 0x80000
	s_lshl_b32 s41, s31, 7
	s_add_u32 s35, s35, s41
	s_add_u32 s0, s66, s35
	s_addc_u32 s1, s67, 0
	s_mul_i32 s35, s31, 0x80000
	s_lshl_b32 s41, s27, 7
	s_add_u32 s35, s35, s41
	s_add_u32 s2, s68, s35
	s_addc_u32 s3, s69, 0
	s_mov_b32 s5, 0x2000
	s_mov_b32 s6, 0x10000
	s_mov_b32 s7, 0x4000
	s_branch .Ltt10_0_r7_e
